# RWKV-7 scan consumer block hand-rescheduled in the original lane layout: y(t-1) chain interleaved with the S.kk chain, DPP hazard slots filled, fewer address/mov ops; same f32 packed math
# speedup vs baseline: 1.0048x; 1.0048x over previous
.LBB0_171:
	s_andn2_b64 vcc, exec, s[36:37]
	s_cbranch_vccnz .LBB0_175
	v_add_u32_e32 v145, s29, v63
	v_add_u32_e32 v145, 0x1000, v145
	ds_read2_b32 v[154:155], v145 offset0:0 offset1:32
	ds_read2_b32 v[156:157], v145 offset0:64 offset1:96
	ds_read2_b32 v[158:159], v145 offset0:128 offset1:160
	ds_read2_b32 v[238:239], v145 offset0:192 offset1:224
	ds_read_b128 v[176:179], v118 offset:24576
	ds_read_b128 v[180:183], v118 offset:24592
	ds_read_b128 v[206:209], v118 offset:16384
	ds_read_b128 v[210:213], v118 offset:16400
	ds_read_b128 v[192:195], v118 offset:8192
	ds_read_b128 v[196:199], v118 offset:8208
	ds_read_b128 v[184:187], v118 offset:32768
	ds_read_b128 v[188:191], v118 offset:32784
	ds_read_b128 v[214:217], v118 offset:0
	ds_read_b128 v[218:221], v118 offset:16
	v_add_u32_e32 v240, s29, v117
	v_add_u32_e32 v240, 0x17000, v240
	s_waitcnt lgkmcnt(6)
	v_pk_mul_f32 v[30:31], v[206:207], v[154:155] op_sel_hi:[1,0]
	v_pk_mul_f32 v[32:33], v[208:209], v[154:155] op_sel_hi:[1,0]
	v_pk_mul_f32 v[34:35], v[210:211], v[154:155] op_sel_hi:[1,0]
	v_pk_mul_f32 v[36:37], v[212:213], v[154:155] op_sel_hi:[1,0]
	v_pk_mul_f32 v[38:39], v[84:85], v[176:177]
	v_pk_fma_f32 v[38:39], v[86:87], v[178:179], v[38:39]
	v_pk_fma_f32 v[38:39], v[88:89], v[180:181], v[38:39]
	v_pk_fma_f32 v[38:39], v[90:91], v[182:183], v[38:39]
	ds_read_b128 v[222:225], v118 offset:24832
	ds_read_b128 v[226:229], v118 offset:24848
	v_add_f32_e32 v42, v38, v39
	s_waitcnt lgkmcnt(7)
	v_pk_fma_f32 v[30:31], v[84:85], v[192:193], v[30:31]
	ds_read_b128 v[130:133], v118 offset:16640
	v_add_f32_dpp v42, v42, v42 quad_perm:[1,0,3,2] row_mask:0xf bank_mask:0xf bound_ctrl:1
	v_pk_fma_f32 v[32:33], v[86:87], v[194:195], v[32:33]
	ds_read_b128 v[134:137], v118 offset:16656
	v_add_f32_dpp v42, v42, v42 quad_perm:[2,3,0,1] row_mask:0xf bank_mask:0xf bound_ctrl:1
	s_waitcnt lgkmcnt(8)
	v_pk_fma_f32 v[34:35], v[88:89], v[196:197], v[34:35]
	ds_read_b128 v[122:125], v118 offset:8448
	v_add_f32_dpp v42, v42, v42 row_half_mirror row_mask:0xf bank_mask:0xf bound_ctrl:1
	v_pk_fma_f32 v[36:37], v[90:91], v[198:199], v[36:37]
	ds_read_b128 v[126:129], v118 offset:8464
	ds_read_b128 v[230:233], v118 offset:33024
	s_waitcnt lgkmcnt(10)
	v_pk_fma_f32 v[84:85], v[184:185], v[42:43], v[30:31] op_sel_hi:[1,0,1]
	v_pk_fma_f32 v[86:87], v[186:187], v[42:43], v[32:33] op_sel_hi:[1,0,1]
	s_waitcnt lgkmcnt(9)
	v_pk_fma_f32 v[88:89], v[188:189], v[42:43], v[34:35] op_sel_hi:[1,0,1]
	v_pk_fma_f32 v[90:91], v[190:191], v[42:43], v[36:37] op_sel_hi:[1,0,1]
	ds_read_b128 v[234:237], v118 offset:33040
	ds_read_b128 v[146:149], v118 offset:256
	ds_read_b128 v[150:153], v118 offset:272
	s_waitcnt lgkmcnt(6)
	v_pk_mul_f32 v[30:31], v[130:131], v[154:155] op_sel:[0,1]
	v_pk_mul_f32 v[32:33], v[132:133], v[154:155] op_sel:[0,1]
	v_pk_mul_f32 v[34:35], v[134:135], v[154:155] op_sel:[0,1]
	v_pk_mul_f32 v[36:37], v[136:137], v[154:155] op_sel:[0,1]
	v_pk_mul_f32 v[38:39], v[84:85], v[222:223]
	v_pk_mul_f32 v[40:41], v[84:85], v[214:215]
	v_pk_fma_f32 v[38:39], v[86:87], v[224:225], v[38:39]
	v_pk_fma_f32 v[40:41], v[86:87], v[216:217], v[40:41]
	v_pk_fma_f32 v[38:39], v[88:89], v[226:227], v[38:39]
	v_pk_fma_f32 v[40:41], v[88:89], v[218:219], v[40:41]
	v_pk_fma_f32 v[38:39], v[90:91], v[228:229], v[38:39]
	v_pk_fma_f32 v[40:41], v[90:91], v[220:221], v[40:41]
	ds_read_b128 v[176:179], v118 offset:25088
	ds_read_b128 v[180:183], v118 offset:25104
	v_add_f32_e32 v42, v38, v39
	v_add_f32_e32 v44, v40, v41
	s_waitcnt lgkmcnt(7)
	v_pk_fma_f32 v[30:31], v[84:85], v[122:123], v[30:31]
	v_add_f32_dpp v42, v42, v42 quad_perm:[1,0,3,2] row_mask:0xf bank_mask:0xf bound_ctrl:1
	v_add_f32_dpp v44, v44, v44 quad_perm:[1,0,3,2] row_mask:0xf bank_mask:0xf bound_ctrl:1
	v_pk_fma_f32 v[32:33], v[86:87], v[124:125], v[32:33]
	v_add_f32_dpp v42, v42, v42 quad_perm:[2,3,0,1] row_mask:0xf bank_mask:0xf bound_ctrl:1
	v_add_f32_dpp v44, v44, v44 quad_perm:[2,3,0,1] row_mask:0xf bank_mask:0xf bound_ctrl:1
	s_waitcnt lgkmcnt(6)
	v_pk_fma_f32 v[34:35], v[88:89], v[126:127], v[34:35]
	v_add_f32_dpp v42, v42, v42 row_half_mirror row_mask:0xf bank_mask:0xf bound_ctrl:1
	v_add_f32_dpp v45, v44, v44 row_half_mirror row_mask:0xf bank_mask:0xf bound_ctrl:1
	v_pk_fma_f32 v[36:37], v[90:91], v[128:129], v[36:37]
	ds_read_b128 v[206:209], v118 offset:16896
	ds_read_b128 v[210:213], v118 offset:16912
	s_waitcnt lgkmcnt(7)
	v_pk_fma_f32 v[84:85], v[230:231], v[42:43], v[30:31] op_sel_hi:[1,0,1]
	v_pk_fma_f32 v[86:87], v[232:233], v[42:43], v[32:33] op_sel_hi:[1,0,1]
	s_waitcnt lgkmcnt(6)
	v_pk_fma_f32 v[88:89], v[234:235], v[42:43], v[34:35] op_sel_hi:[1,0,1]
	v_pk_fma_f32 v[90:91], v[236:237], v[42:43], v[36:37] op_sel_hi:[1,0,1]
	ds_read_b128 v[192:195], v118 offset:8704
	ds_read_b128 v[196:199], v118 offset:8720
	ds_read_b128 v[184:187], v118 offset:33280
	ds_read_b128 v[188:191], v118 offset:33296
	s_waitcnt lgkmcnt(4)
	v_pk_mul_f32 v[30:31], v[206:207], v[156:157] op_sel_hi:[1,0]
	v_pk_mul_f32 v[32:33], v[208:209], v[156:157] op_sel_hi:[1,0]
	v_pk_mul_f32 v[34:35], v[210:211], v[156:157] op_sel_hi:[1,0]
	v_pk_mul_f32 v[36:37], v[212:213], v[156:157] op_sel_hi:[1,0]
	ds_read_b128 v[214:217], v118 offset:512
	ds_read_b128 v[218:221], v118 offset:528
	v_pk_mul_f32 v[38:39], v[84:85], v[176:177]
	v_pk_mul_f32 v[40:41], v[84:85], v[146:147]
	v_pk_fma_f32 v[38:39], v[86:87], v[178:179], v[38:39]
	v_pk_fma_f32 v[40:41], v[86:87], v[148:149], v[40:41]
	v_pk_fma_f32 v[38:39], v[88:89], v[180:181], v[38:39]
	v_pk_fma_f32 v[40:41], v[88:89], v[150:151], v[40:41]
	v_pk_fma_f32 v[38:39], v[90:91], v[182:183], v[38:39]
	v_pk_fma_f32 v[40:41], v[90:91], v[152:153], v[40:41]
	ds_read_b128 v[222:225], v118 offset:25344
	ds_read_b128 v[226:229], v118 offset:25360
	v_add_f32_e32 v42, v38, v39
	v_add_f32_e32 v44, v40, v41
	s_waitcnt lgkmcnt(7)
	v_pk_fma_f32 v[30:31], v[84:85], v[192:193], v[30:31]
	v_add_f32_dpp v42, v42, v42 quad_perm:[1,0,3,2] row_mask:0xf bank_mask:0xf bound_ctrl:1
	v_add_f32_dpp v44, v44, v44 quad_perm:[1,0,3,2] row_mask:0xf bank_mask:0xf bound_ctrl:1
	v_pk_fma_f32 v[32:33], v[86:87], v[194:195], v[32:33]
	v_add_f32_dpp v42, v42, v42 quad_perm:[2,3,0,1] row_mask:0xf bank_mask:0xf bound_ctrl:1
	v_add_f32_dpp v44, v44, v44 quad_perm:[2,3,0,1] row_mask:0xf bank_mask:0xf bound_ctrl:1
	s_waitcnt lgkmcnt(6)
	v_pk_fma_f32 v[34:35], v[88:89], v[196:197], v[34:35]
	v_add_f32_dpp v42, v42, v42 row_half_mirror row_mask:0xf bank_mask:0xf bound_ctrl:1
	v_add_f32_dpp v46, v44, v44 row_half_mirror row_mask:0xf bank_mask:0xf bound_ctrl:1
	v_pk_fma_f32 v[36:37], v[90:91], v[198:199], v[36:37]
	ds_read_b128 v[130:133], v118 offset:17152
	ds_read_b128 v[134:137], v118 offset:17168
	s_waitcnt lgkmcnt(7)
	v_pk_fma_f32 v[84:85], v[184:185], v[42:43], v[30:31] op_sel_hi:[1,0,1]
	v_pk_fma_f32 v[86:87], v[186:187], v[42:43], v[32:33] op_sel_hi:[1,0,1]
	s_waitcnt lgkmcnt(6)
	v_pk_fma_f32 v[88:89], v[188:189], v[42:43], v[34:35] op_sel_hi:[1,0,1]
	v_pk_fma_f32 v[90:91], v[190:191], v[42:43], v[36:37] op_sel_hi:[1,0,1]
	ds_read_b128 v[122:125], v118 offset:8960
	ds_read_b128 v[126:129], v118 offset:8976
	ds_read_b128 v[230:233], v118 offset:33536
	ds_read_b128 v[234:237], v118 offset:33552
	s_waitcnt lgkmcnt(4)
	v_pk_mul_f32 v[30:31], v[130:131], v[156:157] op_sel:[0,1]
	v_pk_mul_f32 v[32:33], v[132:133], v[156:157] op_sel:[0,1]
	v_pk_mul_f32 v[34:35], v[134:135], v[156:157] op_sel:[0,1]
	v_pk_mul_f32 v[36:37], v[136:137], v[156:157] op_sel:[0,1]
	ds_read_b128 v[146:149], v118 offset:768
	ds_read_b128 v[150:153], v118 offset:784
	v_pk_mul_f32 v[38:39], v[84:85], v[222:223]
	v_pk_mul_f32 v[40:41], v[84:85], v[214:215]
	v_pk_fma_f32 v[38:39], v[86:87], v[224:225], v[38:39]
	v_pk_fma_f32 v[40:41], v[86:87], v[216:217], v[40:41]
	v_pk_fma_f32 v[38:39], v[88:89], v[226:227], v[38:39]
	v_pk_fma_f32 v[40:41], v[88:89], v[218:219], v[40:41]
	v_pk_fma_f32 v[38:39], v[90:91], v[228:229], v[38:39]
	v_pk_fma_f32 v[40:41], v[90:91], v[220:221], v[40:41]
	ds_read_b128 v[176:179], v118 offset:25600
	ds_read_b128 v[180:183], v118 offset:25616
	v_add_f32_e32 v42, v38, v39
	v_add_f32_e32 v44, v40, v41
	s_waitcnt lgkmcnt(7)
	v_pk_fma_f32 v[30:31], v[84:85], v[122:123], v[30:31]
	v_add_f32_dpp v42, v42, v42 quad_perm:[1,0,3,2] row_mask:0xf bank_mask:0xf bound_ctrl:1
	v_add_f32_dpp v44, v44, v44 quad_perm:[1,0,3,2] row_mask:0xf bank_mask:0xf bound_ctrl:1
	v_pk_fma_f32 v[32:33], v[86:87], v[124:125], v[32:33]
	v_add_f32_dpp v42, v42, v42 quad_perm:[2,3,0,1] row_mask:0xf bank_mask:0xf bound_ctrl:1
	v_add_f32_dpp v44, v44, v44 quad_perm:[2,3,0,1] row_mask:0xf bank_mask:0xf bound_ctrl:1
	s_waitcnt lgkmcnt(6)
	v_pk_fma_f32 v[34:35], v[88:89], v[126:127], v[34:35]
	v_add_f32_dpp v42, v42, v42 row_half_mirror row_mask:0xf bank_mask:0xf bound_ctrl:1
	v_add_f32_dpp v47, v44, v44 row_half_mirror row_mask:0xf bank_mask:0xf bound_ctrl:1
	v_pk_fma_f32 v[36:37], v[90:91], v[128:129], v[36:37]
	ds_read_b128 v[206:209], v118 offset:17408
	ds_read_b128 v[210:213], v118 offset:17424
	s_waitcnt lgkmcnt(7)
	v_pk_fma_f32 v[84:85], v[230:231], v[42:43], v[30:31] op_sel_hi:[1,0,1]
	v_pk_fma_f32 v[86:87], v[232:233], v[42:43], v[32:33] op_sel_hi:[1,0,1]
	s_waitcnt lgkmcnt(6)
	v_pk_fma_f32 v[88:89], v[234:235], v[42:43], v[34:35] op_sel_hi:[1,0,1]
	v_pk_fma_f32 v[90:91], v[236:237], v[42:43], v[36:37] op_sel_hi:[1,0,1]
	ds_read_b128 v[192:195], v118 offset:9216
	ds_read_b128 v[196:199], v118 offset:9232
	ds_read_b128 v[184:187], v118 offset:33792
	ds_read_b128 v[188:191], v118 offset:33808
	s_waitcnt lgkmcnt(4)
	v_pk_mul_f32 v[30:31], v[206:207], v[158:159] op_sel_hi:[1,0]
	v_pk_mul_f32 v[32:33], v[208:209], v[158:159] op_sel_hi:[1,0]
	v_pk_mul_f32 v[34:35], v[210:211], v[158:159] op_sel_hi:[1,0]
	v_pk_mul_f32 v[36:37], v[212:213], v[158:159] op_sel_hi:[1,0]
	ds_read_b128 v[214:217], v118 offset:1024
	ds_read_b128 v[218:221], v118 offset:1040
	v_pk_mul_f32 v[38:39], v[84:85], v[176:177]
	v_pk_mul_f32 v[40:41], v[84:85], v[146:147]
	v_pk_fma_f32 v[38:39], v[86:87], v[178:179], v[38:39]
	v_pk_fma_f32 v[40:41], v[86:87], v[148:149], v[40:41]
	v_pk_fma_f32 v[38:39], v[88:89], v[180:181], v[38:39]
	v_pk_fma_f32 v[40:41], v[88:89], v[150:151], v[40:41]
	v_pk_fma_f32 v[38:39], v[90:91], v[182:183], v[38:39]
	v_pk_fma_f32 v[40:41], v[90:91], v[152:153], v[40:41]
	ds_read_b128 v[222:225], v118 offset:25856
	ds_read_b128 v[226:229], v118 offset:25872
	v_add_f32_e32 v42, v38, v39
	v_add_f32_e32 v44, v40, v41
	s_waitcnt lgkmcnt(7)
	v_pk_fma_f32 v[30:31], v[84:85], v[192:193], v[30:31]
	v_add_f32_dpp v42, v42, v42 quad_perm:[1,0,3,2] row_mask:0xf bank_mask:0xf bound_ctrl:1
	v_add_f32_dpp v44, v44, v44 quad_perm:[1,0,3,2] row_mask:0xf bank_mask:0xf bound_ctrl:1
	v_pk_fma_f32 v[32:33], v[86:87], v[194:195], v[32:33]
	v_add_f32_dpp v42, v42, v42 quad_perm:[2,3,0,1] row_mask:0xf bank_mask:0xf bound_ctrl:1
	v_add_f32_dpp v44, v44, v44 quad_perm:[2,3,0,1] row_mask:0xf bank_mask:0xf bound_ctrl:1
	s_waitcnt lgkmcnt(6)
	v_pk_fma_f32 v[34:35], v[88:89], v[196:197], v[34:35]
	v_add_f32_dpp v42, v42, v42 row_half_mirror row_mask:0xf bank_mask:0xf bound_ctrl:1
	v_add_f32_dpp v48, v44, v44 row_half_mirror row_mask:0xf bank_mask:0xf bound_ctrl:1
	v_pk_fma_f32 v[36:37], v[90:91], v[198:199], v[36:37]
	ds_read_b128 v[130:133], v118 offset:17664
	ds_read_b128 v[134:137], v118 offset:17680
	s_waitcnt lgkmcnt(7)
	v_pk_fma_f32 v[84:85], v[184:185], v[42:43], v[30:31] op_sel_hi:[1,0,1]
	v_pk_fma_f32 v[86:87], v[186:187], v[42:43], v[32:33] op_sel_hi:[1,0,1]
	s_waitcnt lgkmcnt(6)
	v_pk_fma_f32 v[88:89], v[188:189], v[42:43], v[34:35] op_sel_hi:[1,0,1]
	v_pk_fma_f32 v[90:91], v[190:191], v[42:43], v[36:37] op_sel_hi:[1,0,1]
	ds_read_b128 v[122:125], v118 offset:9472
	ds_read_b128 v[126:129], v118 offset:9488
	ds_read_b128 v[230:233], v118 offset:34048
	ds_read_b128 v[234:237], v118 offset:34064
	s_waitcnt lgkmcnt(4)
	v_pk_mul_f32 v[30:31], v[130:131], v[158:159] op_sel:[0,1]
	v_pk_mul_f32 v[32:33], v[132:133], v[158:159] op_sel:[0,1]
	v_pk_mul_f32 v[34:35], v[134:135], v[158:159] op_sel:[0,1]
	v_pk_mul_f32 v[36:37], v[136:137], v[158:159] op_sel:[0,1]
	ds_read_b128 v[146:149], v118 offset:1280
	ds_read_b128 v[150:153], v118 offset:1296
	v_pk_mul_f32 v[38:39], v[84:85], v[222:223]
	v_pk_mul_f32 v[40:41], v[84:85], v[214:215]
	v_pk_fma_f32 v[38:39], v[86:87], v[224:225], v[38:39]
	v_pk_fma_f32 v[40:41], v[86:87], v[216:217], v[40:41]
	v_pk_fma_f32 v[38:39], v[88:89], v[226:227], v[38:39]
	v_pk_fma_f32 v[40:41], v[88:89], v[218:219], v[40:41]
	v_pk_fma_f32 v[38:39], v[90:91], v[228:229], v[38:39]
	v_pk_fma_f32 v[40:41], v[90:91], v[220:221], v[40:41]
	ds_read_b128 v[176:179], v118 offset:26112
	ds_read_b128 v[180:183], v118 offset:26128
	v_add_f32_e32 v42, v38, v39
	v_add_f32_e32 v44, v40, v41
	s_waitcnt lgkmcnt(7)
	v_pk_fma_f32 v[30:31], v[84:85], v[122:123], v[30:31]
	v_add_f32_dpp v42, v42, v42 quad_perm:[1,0,3,2] row_mask:0xf bank_mask:0xf bound_ctrl:1
	v_add_f32_dpp v44, v44, v44 quad_perm:[1,0,3,2] row_mask:0xf bank_mask:0xf bound_ctrl:1
	v_pk_fma_f32 v[32:33], v[86:87], v[124:125], v[32:33]
	v_add_f32_dpp v42, v42, v42 quad_perm:[2,3,0,1] row_mask:0xf bank_mask:0xf bound_ctrl:1
	v_add_f32_dpp v44, v44, v44 quad_perm:[2,3,0,1] row_mask:0xf bank_mask:0xf bound_ctrl:1
	s_waitcnt lgkmcnt(6)
	v_pk_fma_f32 v[34:35], v[88:89], v[126:127], v[34:35]
	v_add_f32_dpp v42, v42, v42 row_half_mirror row_mask:0xf bank_mask:0xf bound_ctrl:1
	v_add_f32_dpp v49, v44, v44 row_half_mirror row_mask:0xf bank_mask:0xf bound_ctrl:1
	v_pk_fma_f32 v[36:37], v[90:91], v[128:129], v[36:37]
	ds_read_b128 v[206:209], v118 offset:17920
	ds_read_b128 v[210:213], v118 offset:17936
	s_waitcnt lgkmcnt(7)
	v_pk_fma_f32 v[84:85], v[230:231], v[42:43], v[30:31] op_sel_hi:[1,0,1]
	v_pk_fma_f32 v[86:87], v[232:233], v[42:43], v[32:33] op_sel_hi:[1,0,1]
	s_waitcnt lgkmcnt(6)
	v_pk_fma_f32 v[88:89], v[234:235], v[42:43], v[34:35] op_sel_hi:[1,0,1]
	v_pk_fma_f32 v[90:91], v[236:237], v[42:43], v[36:37] op_sel_hi:[1,0,1]
	ds_read_b128 v[192:195], v118 offset:9728
	ds_read_b128 v[196:199], v118 offset:9744
	ds_read_b128 v[184:187], v118 offset:34304
	ds_read_b128 v[188:191], v118 offset:34320
	s_waitcnt lgkmcnt(4)
	v_pk_mul_f32 v[30:31], v[206:207], v[238:239] op_sel_hi:[1,0]
	v_pk_mul_f32 v[32:33], v[208:209], v[238:239] op_sel_hi:[1,0]
	v_pk_mul_f32 v[34:35], v[210:211], v[238:239] op_sel_hi:[1,0]
	v_pk_mul_f32 v[36:37], v[212:213], v[238:239] op_sel_hi:[1,0]
	ds_read_b128 v[214:217], v118 offset:1536
	ds_read_b128 v[218:221], v118 offset:1552
	v_pk_mul_f32 v[38:39], v[84:85], v[176:177]
	v_pk_mul_f32 v[40:41], v[84:85], v[146:147]
	v_pk_fma_f32 v[38:39], v[86:87], v[178:179], v[38:39]
	v_pk_fma_f32 v[40:41], v[86:87], v[148:149], v[40:41]
	v_pk_fma_f32 v[38:39], v[88:89], v[180:181], v[38:39]
	v_pk_fma_f32 v[40:41], v[88:89], v[150:151], v[40:41]
	v_pk_fma_f32 v[38:39], v[90:91], v[182:183], v[38:39]
	v_pk_fma_f32 v[40:41], v[90:91], v[152:153], v[40:41]
	ds_read_b128 v[222:225], v118 offset:26368
	ds_read_b128 v[226:229], v118 offset:26384
	v_add_f32_e32 v42, v38, v39
	v_add_f32_e32 v44, v40, v41
	s_waitcnt lgkmcnt(7)
	v_pk_fma_f32 v[30:31], v[84:85], v[192:193], v[30:31]
	v_add_f32_dpp v42, v42, v42 quad_perm:[1,0,3,2] row_mask:0xf bank_mask:0xf bound_ctrl:1
	v_add_f32_dpp v44, v44, v44 quad_perm:[1,0,3,2] row_mask:0xf bank_mask:0xf bound_ctrl:1
	v_pk_fma_f32 v[32:33], v[86:87], v[194:195], v[32:33]
	v_add_f32_dpp v42, v42, v42 quad_perm:[2,3,0,1] row_mask:0xf bank_mask:0xf bound_ctrl:1
	v_add_f32_dpp v44, v44, v44 quad_perm:[2,3,0,1] row_mask:0xf bank_mask:0xf bound_ctrl:1
	s_waitcnt lgkmcnt(6)
	v_pk_fma_f32 v[34:35], v[88:89], v[196:197], v[34:35]
	v_add_f32_dpp v42, v42, v42 row_half_mirror row_mask:0xf bank_mask:0xf bound_ctrl:1
	v_add_f32_dpp v200, v44, v44 row_half_mirror row_mask:0xf bank_mask:0xf bound_ctrl:1
	v_pk_fma_f32 v[36:37], v[90:91], v[198:199], v[36:37]
	ds_read_b128 v[130:133], v118 offset:18176
	ds_read_b128 v[134:137], v118 offset:18192
	s_waitcnt lgkmcnt(7)
	v_pk_fma_f32 v[84:85], v[184:185], v[42:43], v[30:31] op_sel_hi:[1,0,1]
	v_pk_fma_f32 v[86:87], v[186:187], v[42:43], v[32:33] op_sel_hi:[1,0,1]
	s_waitcnt lgkmcnt(6)
	v_pk_fma_f32 v[88:89], v[188:189], v[42:43], v[34:35] op_sel_hi:[1,0,1]
	v_pk_fma_f32 v[90:91], v[190:191], v[42:43], v[36:37] op_sel_hi:[1,0,1]
	ds_read_b128 v[122:125], v118 offset:9984
	ds_read_b128 v[126:129], v118 offset:10000
	ds_read_b128 v[230:233], v118 offset:34560
	ds_read_b128 v[234:237], v118 offset:34576
	s_waitcnt lgkmcnt(4)
	v_pk_mul_f32 v[30:31], v[130:131], v[238:239] op_sel:[0,1]
	v_pk_mul_f32 v[32:33], v[132:133], v[238:239] op_sel:[0,1]
	v_pk_mul_f32 v[34:35], v[134:135], v[238:239] op_sel:[0,1]
	v_pk_mul_f32 v[36:37], v[136:137], v[238:239] op_sel:[0,1]
	ds_read_b128 v[146:149], v118 offset:1792
	ds_read_b128 v[150:153], v118 offset:1808
	v_pk_mul_f32 v[38:39], v[84:85], v[222:223]
	v_pk_mul_f32 v[40:41], v[84:85], v[214:215]
	v_pk_fma_f32 v[38:39], v[86:87], v[224:225], v[38:39]
	v_pk_fma_f32 v[40:41], v[86:87], v[216:217], v[40:41]
	v_pk_fma_f32 v[38:39], v[88:89], v[226:227], v[38:39]
	v_pk_fma_f32 v[40:41], v[88:89], v[218:219], v[40:41]
	v_pk_fma_f32 v[38:39], v[90:91], v[228:229], v[38:39]
	v_pk_fma_f32 v[40:41], v[90:91], v[220:221], v[40:41]
	v_add_f32_e32 v42, v38, v39
	v_add_f32_e32 v44, v40, v41
	s_waitcnt lgkmcnt(5)
	v_pk_fma_f32 v[30:31], v[84:85], v[122:123], v[30:31]
	v_add_f32_dpp v42, v42, v42 quad_perm:[1,0,3,2] row_mask:0xf bank_mask:0xf bound_ctrl:1
	v_add_f32_dpp v44, v44, v44 quad_perm:[1,0,3,2] row_mask:0xf bank_mask:0xf bound_ctrl:1
	v_pk_fma_f32 v[32:33], v[86:87], v[124:125], v[32:33]
	v_add_f32_dpp v42, v42, v42 quad_perm:[2,3,0,1] row_mask:0xf bank_mask:0xf bound_ctrl:1
	v_add_f32_dpp v44, v44, v44 quad_perm:[2,3,0,1] row_mask:0xf bank_mask:0xf bound_ctrl:1
	s_waitcnt lgkmcnt(4)
	v_pk_fma_f32 v[34:35], v[88:89], v[126:127], v[34:35]
	v_add_f32_dpp v42, v42, v42 row_half_mirror row_mask:0xf bank_mask:0xf bound_ctrl:1
	v_add_f32_dpp v201, v44, v44 row_half_mirror row_mask:0xf bank_mask:0xf bound_ctrl:1
	v_pk_fma_f32 v[36:37], v[90:91], v[128:129], v[36:37]
	s_waitcnt lgkmcnt(3)
	v_pk_fma_f32 v[84:85], v[230:231], v[42:43], v[30:31] op_sel_hi:[1,0,1]
	v_pk_fma_f32 v[86:87], v[232:233], v[42:43], v[32:33] op_sel_hi:[1,0,1]
	s_waitcnt lgkmcnt(2)
	v_pk_fma_f32 v[88:89], v[234:235], v[42:43], v[34:35] op_sel_hi:[1,0,1]
	v_pk_fma_f32 v[90:91], v[236:237], v[42:43], v[36:37] op_sel_hi:[1,0,1]
	s_waitcnt lgkmcnt(1)
	v_pk_mul_f32 v[40:41], v[84:85], v[146:147]
	v_pk_fma_f32 v[40:41], v[86:87], v[148:149], v[40:41]
	s_waitcnt lgkmcnt(0)
	v_pk_fma_f32 v[40:41], v[88:89], v[150:151], v[40:41]
	v_pk_fma_f32 v[40:41], v[90:91], v[152:153], v[40:41]
	v_add_f32_e32 v44, v40, v41
	s_nop 1
	v_add_f32_dpp v44, v44, v44 quad_perm:[1,0,3,2] row_mask:0xf bank_mask:0xf bound_ctrl:1
	s_nop 1
	v_add_f32_dpp v44, v44, v44 quad_perm:[2,3,0,1] row_mask:0xf bank_mask:0xf bound_ctrl:1
	s_nop 1
	v_add_f32_dpp v202, v44, v44 row_half_mirror row_mask:0xf bank_mask:0xf bound_ctrl:1
	s_and_saveexec_b64 s[46:47], s[12:13]
	ds_write_b32 v240, v45 offset:0
	ds_write_b32 v240, v46 offset:128
	ds_write_b32 v240, v47 offset:256
	ds_write_b32 v240, v48 offset:384
	ds_write_b32 v240, v49 offset:512
	ds_write_b32 v240, v200 offset:640
	ds_write_b32 v240, v201 offset:768
	ds_write_b32 v240, v202 offset:896
